# V^T epilogue: dilation-4 scatter also if-converted (2 full-exec dwordx2 stores per 16-row group)
# baseline (speedup 1.0000x reference)
.LBB0_218:
	s_lshl_b32 s13, s33, 8
	v_or_b32_e32 v168, s13, v181
	v_ashrrev_i32_e32 v169, 31, v168
	v_lshl_add_u64 v[44:45], v[168:169], 2, s[64:65]
	global_load_dwordx4 v[52:55], v[44:45], off
	global_load_dwordx4 v[48:51], v[44:45], off offset:16
	global_load_dwordx4 v[40:43], v[44:45], off offset:528
	s_nop 0
	global_load_dwordx4 v[44:47], v[44:45], off offset:512
	v_lshl_add_u32 v186, s12, 8, v155
	v_mov_b64_e32 v[170:171], s[28:29]
	s_cmp_gt_i32 s12, 1
	v_mad_i64_i32 v[170:171], s[74:75], v186, s61, v[170:171]
	s_cselect_b64 s[76:77], -1, 0
	s_ashr_i32 s74, s33, 5
	s_ashr_i32 s75, s74, 31
	s_and_b32 s13, s13, 0x1f00
	s_lshl_b64 s[74:75], s[74:75], 13
	v_add_u32_e32 v152, 0xfffffe00, v186
	s_or_b32 s33, s13, s51
	v_lshl_add_u64 v[174:175], v[168:169], 1, v[170:171]
	v_mov_b64_e32 v[170:171], s[74:75]
	s_cmp_lt_i32 s12, 2
	v_mad_i64_i32 v[170:171], s[12:13], v152, s54, v[170:171]
	v_lshl_add_u64 v[172:173], v[170:171], 1, s[20:21]
	v_lshlrev_b32_e32 v152, 1, v154
	s_waitcnt vmcnt(0)
	v_pk_mul_f32 v[142:143], v[142:143], v[54:55]
	v_pk_mul_f32 v[140:141], v[140:141], v[52:53]
	v_pk_mul_f32 v[176:177], v[138:139], v[50:51]
	v_pk_mul_f32 v[138:139], v[136:137], v[48:49]
	v_cvt_pk_bf16_f32 v136, v140, v141
	v_cvt_pk_bf16_f32 v137, v142, v143
	v_cvt_pk_bf16_f32 v138, v138, v139
	v_cvt_pk_bf16_f32 v139, v176, v177
	global_store_dwordx4 v[174:175], v[136:139], off
	s_cbranch_scc1 .LBB0_228
	v_and_b32_e32 v177, 64, v185
	v_xor_b32_e32 v143, 16, v185
	v_add_u32_e32 v195, 64, v177
	v_and_b32_e32 v187, 0xffff, v136
	v_lshlrev_b32_e32 v194, 16, v138
	v_lshrrev_b32_e32 v188, 16, v136
	v_and_b32_e32 v191, 0xffff0000, v138
	v_and_b32_e32 v189, 0xffff, v137
	v_lshlrev_b32_e32 v192, 16, v139
	v_lshrrev_b32_e32 v190, 16, v137
	v_and_b32_e32 v193, 0xffff0000, v139
	v_cmp_lt_i32_e32 vcc, v143, v195
	v_or_b32_e32 v142, v194, v187
	v_or_b32_e32 v196, v191, v188
	v_or_b32_e32 v179, v192, v189
	v_or_b32_e32 v141, v193, v190
	v_cndmask_b32_e32 v143, v185, v143, vcc
	v_cndmask_b32_e64 v140, v142, v179, s[2:3]
	v_cndmask_b32_e64 v176, v196, v141, s[2:3]
	v_lshlrev_b32_e32 v177, 2, v143
	ds_bpermute_b32 v143, v177, v140
	ds_bpermute_b32 v197, v177, v176
	s_lshr_b32 s36, s33, 1
	v_lshl_add_u64 v[176:177], v[172:173], 0, s[36:37]
	v_lshl_add_u64 v[176:177], v[176:177], 0, v[152:153]
	s_waitcnt lgkmcnt(0)
	v_cndmask_b32_e64 v232, v142, v143, s[4:5]
	v_cndmask_b32_e64 v233, v143, v179, s[4:5]
	v_cndmask_b32_e64 v234, v196, v197, s[4:5]
	v_cndmask_b32_e64 v235, v197, v141, s[4:5]
	v_mov_b32_e32 v240, 0x2000
	v_mov_b32_e32 v241, 0
	v_cndmask_b32_e64 v240, 0, v240, s[4:5]
	v_lshl_add_u64 v[236:237], v[176:177], 0, v[240:241]
	global_store_dwordx2 v[236:237], v[232:233], off
	v_mov_b32_e32 v240, 0x1000
	v_lshl_add_u64 v[238:239], v[236:237], 0, v[240:241]
	global_store_dwordx2 v[238:239], v[234:235], off
	v_cndmask_b32_e64 v136, v136, v138, s[6:7]
	v_xor_b32_e32 v138, 32, v185
	v_cmp_lt_i32_e32 vcc, v138, v195
	v_cndmask_b32_e64 v137, v137, v139, s[6:7]
	s_lshr_b32 s36, s33, 3
	v_cndmask_b32_e32 v138, v185, v138, vcc
	v_lshlrev_b32_e32 v138, 2, v138
	ds_bpermute_b32 v143, v138, v136
	ds_bpermute_b32 v142, v138, v137
	v_lshl_add_u64 v[136:137], v[170:171], 1, v[156:157]
	v_lshl_add_u64 v[136:137], v[136:137], 0, s[36:37]
	s_waitcnt lgkmcnt(0)
	v_and_or_b32 v232, v143, s62, v194
	v_or_b32_sdwa v233, v143, v191 dst_sel:DWORD dst_unused:UNUSED_PAD src0_sel:WORD_1 src1_sel:DWORD
	v_and_or_b32 v234, v142, s62, v192
	v_or_b32_sdwa v235, v142, v193 dst_sel:DWORD dst_unused:UNUSED_PAD src0_sel:WORD_1 src1_sel:DWORD
	v_lshl_or_b32 v236, v143, 16, v187
	v_and_or_b32 v237, v143, s63, v188
	v_lshl_or_b32 v238, v142, 16, v189
	v_and_or_b32 v239, v142, s63, v190
	v_mov_b32_e32 v240, 0x1000
	v_mov_b32_e32 v241, 0
	v_cndmask_b32_e64 v232, v236, v232, s[8:9]
	v_cndmask_b32_e64 v233, v237, v233, s[8:9]
	v_cndmask_b32_e64 v234, v238, v234, s[8:9]
	v_cndmask_b32_e64 v235, v239, v235, s[8:9]
	v_cndmask_b32_e64 v240, 0, v240, s[8:9]
	v_lshl_add_u64 v[136:137], v[136:137], 0, v[240:241]
	global_store_dword v[136:137], v232, off
	global_store_dword v[136:137], v233, off offset:1024
	global_store_dword v[136:137], v234, off offset:2048
	global_store_dword v[136:137], v235, off offset:3072
.LBB0_228:
	v_pk_mul_f32 v[132:133], v[132:133], v[44:45]
	v_pk_mul_f32 v[134:135], v[134:135], v[46:47]
	v_pk_mul_f32 v[136:137], v[130:131], v[42:43]
	v_pk_mul_f32 v[130:131], v[128:129], v[40:41]
	v_cvt_pk_bf16_f32 v128, v132, v133
	v_cndmask_b32_e64 v132, 0, 1, s[76:77]
	v_cvt_pk_bf16_f32 v129, v134, v135
	v_cvt_pk_bf16_f32 v130, v130, v131
	v_cvt_pk_bf16_f32 v131, v136, v137
	v_cmp_ne_u32_e64 s[12:13], 1, v132
	s_andn2_b64 vcc, exec, s[76:77]
	global_store_dwordx4 v[174:175], v[128:131], off offset:256
	s_cbranch_vccnz .LBB0_238
	v_and_b32_e32 v138, 64, v185
	v_xor_b32_e32 v134, 16, v185
	v_add_u32_e32 v187, 64, v138
	s_waitcnt lgkmcnt(0)
	v_and_b32_e32 v142, 0xffff, v128
	v_lshlrev_b32_e32 v179, 16, v130
	v_lshrrev_b32_e32 v143, 16, v128
	v_and_b32_e32 v176, 0xffff0000, v130
	v_and_b32_e32 v174, 0xffff, v129
	v_lshlrev_b32_e32 v177, 16, v131
	v_lshrrev_b32_e32 v175, 16, v129
	v_and_b32_e32 v178, 0xffff0000, v131
	v_cmp_lt_i32_e32 vcc, v134, v187
	v_or_b32_e32 v136, v179, v142
	v_or_b32_e32 v189, v176, v143
	v_or_b32_e32 v135, v177, v174
	v_or_b32_e32 v133, v178, v175
	v_cndmask_b32_e32 v134, v185, v134, vcc
	v_cndmask_b32_e64 v132, v136, v135, s[2:3]
	v_cndmask_b32_e64 v137, v189, v133, s[2:3]
	v_lshlrev_b32_e32 v138, 2, v134
	ds_bpermute_b32 v134, v138, v132
	ds_bpermute_b32 v188, v138, v137
	s_or_b32 s34, s33, 0x80
	s_lshr_b32 s36, s34, 1
	v_lshl_add_u64 v[138:139], v[172:173], 0, s[36:37]
	v_lshl_add_u64 v[138:139], v[138:139], 0, v[152:153]
	s_waitcnt lgkmcnt(0)
	v_cndmask_b32_e64 v232, v136, v134, s[4:5]
	v_cndmask_b32_e64 v233, v134, v135, s[4:5]
	v_cndmask_b32_e64 v234, v189, v188, s[4:5]
	v_cndmask_b32_e64 v235, v188, v133, s[4:5]
	v_mov_b32_e32 v240, 0x2000
	v_mov_b32_e32 v241, 0
	v_cndmask_b32_e64 v240, 0, v240, s[4:5]
	v_lshl_add_u64 v[236:237], v[138:139], 0, v[240:241]
	global_store_dwordx2 v[236:237], v[232:233], off
	v_mov_b32_e32 v240, 0x1000
	v_lshl_add_u64 v[238:239], v[236:237], 0, v[240:241]
	global_store_dwordx2 v[238:239], v[234:235], off
	v_cndmask_b32_e64 v128, v128, v130, s[6:7]
	v_xor_b32_e32 v130, 32, v185
	v_cmp_lt_i32_e32 vcc, v130, v187
	v_cndmask_b32_e64 v129, v129, v131, s[6:7]
	s_lshr_b32 s36, s34, 3
	v_cndmask_b32_e32 v130, v185, v130, vcc
	v_lshlrev_b32_e32 v130, 2, v130
	ds_bpermute_b32 v135, v130, v128
	ds_bpermute_b32 v134, v130, v129
	v_lshl_add_u64 v[128:129], v[170:171], 1, v[156:157]
	v_lshl_add_u64 v[128:129], v[128:129], 0, s[36:37]
	s_waitcnt lgkmcnt(0)
	v_and_or_b32 v232, v135, s62, v179
	v_or_b32_sdwa v233, v135, v176 dst_sel:DWORD dst_unused:UNUSED_PAD src0_sel:WORD_1 src1_sel:DWORD
	v_and_or_b32 v234, v134, s62, v177
	v_or_b32_sdwa v235, v134, v178 dst_sel:DWORD dst_unused:UNUSED_PAD src0_sel:WORD_1 src1_sel:DWORD
	v_lshl_or_b32 v236, v135, 16, v142
	v_and_or_b32 v237, v135, s63, v143
	v_lshl_or_b32 v238, v134, 16, v174
	v_and_or_b32 v239, v134, s63, v175
	v_mov_b32_e32 v240, 0x1000
	v_mov_b32_e32 v241, 0
	v_cndmask_b32_e64 v232, v236, v232, s[8:9]
	v_cndmask_b32_e64 v233, v237, v233, s[8:9]
	v_cndmask_b32_e64 v234, v238, v234, s[8:9]
	v_cndmask_b32_e64 v235, v239, v235, s[8:9]
	v_cndmask_b32_e64 v240, 0, v240, s[8:9]
	v_lshl_add_u64 v[128:129], v[128:129], 0, v[240:241]
	global_store_dword v[128:129], v232, off
	global_store_dword v[128:129], v233, off offset:1024
	global_store_dword v[128:129], v234, off offset:2048
	global_store_dword v[128:129], v235, off offset:3072
.LBB0_238:
	s_nop 0
	v_or_b32_e32 v130, 16, v186
	v_mov_b64_e32 v[128:129], s[28:29]
	v_mad_i64_i32 v[128:129], s[76:77], v130, s61, v[128:129]
	v_lshl_add_u64 v[130:131], v[168:169], 1, v[128:129]
	v_add_u32_e32 v132, 0xfffffe10, v186
	v_mov_b64_e32 v[128:129], s[74:75]
	v_mad_i64_i32 v[128:129], s[76:77], v132, s54, v[128:129]
	v_pk_mul_f32 v[126:127], v[126:127], v[54:55]
	v_pk_mul_f32 v[124:125], v[124:125], v[52:53]
	v_pk_mul_f32 v[132:133], v[122:123], v[50:51]
	v_pk_mul_f32 v[122:123], v[120:121], v[48:49]
	v_cvt_pk_bf16_f32 v120, v124, v125
	v_cvt_pk_bf16_f32 v121, v126, v127
	v_cvt_pk_bf16_f32 v122, v122, v123
	v_cvt_pk_bf16_f32 v123, v132, v133
	s_and_b64 vcc, exec, s[12:13]
	v_lshl_add_u64 v[124:125], v[128:129], 1, s[20:21]
	global_store_dwordx4 v[130:131], v[120:123], off
	s_cbranch_vccnz .LBB0_248
	v_and_b32_e32 v136, 64, v185
	v_xor_b32_e32 v132, 16, v185
	v_add_u32_e32 v174, 64, v136
	v_and_b32_e32 v140, 0xffff, v120
	v_lshlrev_b32_e32 v173, 16, v122
	v_lshrrev_b32_e32 v141, 16, v120
	v_and_b32_e32 v170, 0xffff0000, v122
	s_waitcnt lgkmcnt(0)
	v_and_b32_e32 v142, 0xffff, v121
	v_lshlrev_b32_e32 v171, 16, v123
	v_lshrrev_b32_e32 v143, 16, v121
	v_and_b32_e32 v172, 0xffff0000, v123
	v_cmp_lt_i32_e32 vcc, v132, v174
	v_or_b32_e32 v134, v173, v140
	v_or_b32_e32 v175, v170, v141
	v_or_b32_e32 v133, v171, v142
	v_or_b32_e32 v127, v172, v143
	v_cndmask_b32_e32 v132, v185, v132, vcc
	v_cndmask_b32_e64 v126, v134, v133, s[2:3]
	v_cndmask_b32_e64 v135, v175, v127, s[2:3]
	v_lshlrev_b32_e32 v136, 2, v132
	ds_bpermute_b32 v132, v136, v126
	ds_bpermute_b32 v176, v136, v135
	s_lshr_b32 s36, s33, 1
	v_lshl_add_u64 v[136:137], v[124:125], 0, s[36:37]
	v_lshl_add_u64 v[136:137], v[136:137], 0, v[152:153]
	s_waitcnt lgkmcnt(0)
	v_cndmask_b32_e64 v232, v134, v132, s[4:5]
	v_cndmask_b32_e64 v233, v132, v133, s[4:5]
	v_cndmask_b32_e64 v234, v175, v176, s[4:5]
	v_cndmask_b32_e64 v235, v176, v127, s[4:5]
	v_mov_b32_e32 v240, 0x2000
	v_mov_b32_e32 v241, 0
	v_cndmask_b32_e64 v240, 0, v240, s[4:5]
	v_lshl_add_u64 v[236:237], v[136:137], 0, v[240:241]
	global_store_dwordx2 v[236:237], v[232:233], off
	v_mov_b32_e32 v240, 0x1000
	v_lshl_add_u64 v[238:239], v[236:237], 0, v[240:241]
	global_store_dwordx2 v[238:239], v[234:235], off
	v_cndmask_b32_e64 v120, v120, v122, s[6:7]
	v_xor_b32_e32 v122, 32, v185
	v_cmp_lt_i32_e32 vcc, v122, v174
	v_cndmask_b32_e64 v121, v121, v123, s[6:7]
	s_lshr_b32 s36, s33, 3
	v_cndmask_b32_e32 v122, v185, v122, vcc
	v_lshlrev_b32_e32 v122, 2, v122
	ds_bpermute_b32 v133, v122, v120
	ds_bpermute_b32 v132, v122, v121
	v_lshl_add_u64 v[120:121], v[128:129], 1, v[156:157]
	v_lshl_add_u64 v[120:121], v[120:121], 0, s[36:37]
	s_waitcnt lgkmcnt(0)
	v_and_or_b32 v232, v133, s62, v173
	v_or_b32_sdwa v233, v133, v170 dst_sel:DWORD dst_unused:UNUSED_PAD src0_sel:WORD_1 src1_sel:DWORD
	v_and_or_b32 v234, v132, s62, v171
	v_or_b32_sdwa v235, v132, v172 dst_sel:DWORD dst_unused:UNUSED_PAD src0_sel:WORD_1 src1_sel:DWORD
	v_lshl_or_b32 v236, v133, 16, v140
	v_and_or_b32 v237, v133, s63, v141
	v_lshl_or_b32 v238, v132, 16, v142
	v_and_or_b32 v239, v132, s63, v143
	v_mov_b32_e32 v240, 0x1000
	v_mov_b32_e32 v241, 0
	v_cndmask_b32_e64 v232, v236, v232, s[8:9]
	v_cndmask_b32_e64 v233, v237, v233, s[8:9]
	v_cndmask_b32_e64 v234, v238, v234, s[8:9]
	v_cndmask_b32_e64 v235, v239, v235, s[8:9]
	v_cndmask_b32_e64 v240, 0, v240, s[8:9]
	v_lshl_add_u64 v[120:121], v[120:121], 0, v[240:241]
	global_store_dword v[120:121], v232, off
	global_store_dword v[120:121], v233, off offset:1024
	global_store_dword v[120:121], v234, off offset:2048
	global_store_dword v[120:121], v235, off offset:3072
.LBB0_248:
	v_pk_mul_f32 v[118:119], v[118:119], v[46:47]
	v_pk_mul_f32 v[116:117], v[116:117], v[44:45]
	v_pk_mul_f32 v[120:121], v[114:115], v[42:43]
	v_pk_mul_f32 v[114:115], v[112:113], v[40:41]
	v_cvt_pk_bf16_f32 v112, v116, v117
	v_cvt_pk_bf16_f32 v113, v118, v119
	v_cvt_pk_bf16_f32 v114, v114, v115
	v_cvt_pk_bf16_f32 v115, v120, v121
	s_and_b64 vcc, exec, s[12:13]
	global_store_dwordx4 v[130:131], v[112:115], off offset:256
	s_cbranch_vccnz .LBB0_258
	v_and_b32_e32 v122, 64, v185
	v_xor_b32_e32 v118, 16, v185
	v_add_u32_e32 v136, 64, v122
	v_and_b32_e32 v126, 0xffff, v112
	s_waitcnt lgkmcnt(1)
	v_lshlrev_b32_e32 v135, 16, v114
	v_lshrrev_b32_e32 v127, 16, v112
	s_waitcnt lgkmcnt(0)
	v_and_b32_e32 v132, 0xffff0000, v114
	v_and_b32_e32 v130, 0xffff, v113
	v_lshlrev_b32_e32 v133, 16, v115
	v_lshrrev_b32_e32 v131, 16, v113
	v_and_b32_e32 v134, 0xffff0000, v115
	v_cmp_lt_i32_e32 vcc, v118, v136
	v_or_b32_e32 v120, v135, v126
	v_or_b32_e32 v138, v132, v127
	v_or_b32_e32 v119, v133, v130
	v_or_b32_e32 v117, v134, v131
	v_cndmask_b32_e32 v118, v185, v118, vcc
	v_cndmask_b32_e64 v116, v120, v119, s[2:3]
	v_cndmask_b32_e64 v121, v138, v117, s[2:3]
	v_lshlrev_b32_e32 v122, 2, v118
	ds_bpermute_b32 v118, v122, v116
	ds_bpermute_b32 v137, v122, v121
	s_or_b32 s34, s33, 0x80
	s_lshr_b32 s36, s34, 1
	v_lshl_add_u64 v[122:123], v[124:125], 0, s[36:37]
	v_lshl_add_u64 v[122:123], v[122:123], 0, v[152:153]
	s_waitcnt lgkmcnt(0)
	v_cndmask_b32_e64 v232, v120, v118, s[4:5]
	v_cndmask_b32_e64 v233, v118, v119, s[4:5]
	v_cndmask_b32_e64 v234, v138, v137, s[4:5]
	v_cndmask_b32_e64 v235, v137, v117, s[4:5]
	v_mov_b32_e32 v240, 0x2000
	v_mov_b32_e32 v241, 0
	v_cndmask_b32_e64 v240, 0, v240, s[4:5]
	v_lshl_add_u64 v[236:237], v[122:123], 0, v[240:241]
	global_store_dwordx2 v[236:237], v[232:233], off
	v_mov_b32_e32 v240, 0x1000
	v_lshl_add_u64 v[238:239], v[236:237], 0, v[240:241]
	global_store_dwordx2 v[238:239], v[234:235], off
	v_cndmask_b32_e64 v112, v112, v114, s[6:7]
	v_xor_b32_e32 v114, 32, v185
	v_cmp_lt_i32_e32 vcc, v114, v136
	v_cndmask_b32_e64 v113, v113, v115, s[6:7]
	s_lshr_b32 s36, s34, 3
	v_cndmask_b32_e32 v114, v185, v114, vcc
	v_lshlrev_b32_e32 v114, 2, v114
	ds_bpermute_b32 v119, v114, v112
	ds_bpermute_b32 v118, v114, v113
	v_lshl_add_u64 v[112:113], v[128:129], 1, v[156:157]
	v_lshl_add_u64 v[112:113], v[112:113], 0, s[36:37]
	s_waitcnt lgkmcnt(0)
	v_and_or_b32 v232, v119, s62, v135
	v_or_b32_sdwa v233, v119, v132 dst_sel:DWORD dst_unused:UNUSED_PAD src0_sel:WORD_1 src1_sel:DWORD
	v_and_or_b32 v234, v118, s62, v133
	v_or_b32_sdwa v235, v118, v134 dst_sel:DWORD dst_unused:UNUSED_PAD src0_sel:WORD_1 src1_sel:DWORD
	v_lshl_or_b32 v236, v119, 16, v126
	v_and_or_b32 v237, v119, s63, v127
	v_lshl_or_b32 v238, v118, 16, v130
	v_and_or_b32 v239, v118, s63, v131
	v_mov_b32_e32 v240, 0x1000
	v_mov_b32_e32 v241, 0
	v_cndmask_b32_e64 v232, v236, v232, s[8:9]
	v_cndmask_b32_e64 v233, v237, v233, s[8:9]
	v_cndmask_b32_e64 v234, v238, v234, s[8:9]
	v_cndmask_b32_e64 v235, v239, v235, s[8:9]
	v_cndmask_b32_e64 v240, 0, v240, s[8:9]
	v_lshl_add_u64 v[112:113], v[112:113], 0, v[240:241]
	global_store_dword v[112:113], v232, off
	global_store_dword v[112:113], v233, off offset:1024
	global_store_dword v[112:113], v234, off offset:2048
	global_store_dword v[112:113], v235, off offset:3072
.LBB0_258:
	s_nop 0
	v_or_b32_e32 v114, 32, v186
	v_mov_b64_e32 v[112:113], s[28:29]
	v_mad_i64_i32 v[112:113], s[76:77], v114, s61, v[112:113]
	v_lshl_add_u64 v[114:115], v[168:169], 1, v[112:113]
	v_add_u32_e32 v116, 0xfffffe20, v186
	v_mov_b64_e32 v[112:113], s[74:75]
	v_mad_i64_i32 v[112:113], s[76:77], v116, s54, v[112:113]
	v_pk_mul_f32 v[110:111], v[110:111], v[54:55]
	v_pk_mul_f32 v[108:109], v[108:109], v[52:53]
	v_pk_mul_f32 v[116:117], v[106:107], v[50:51]
	v_pk_mul_f32 v[106:107], v[104:105], v[48:49]
	v_cvt_pk_bf16_f32 v104, v108, v109
	v_cvt_pk_bf16_f32 v105, v110, v111
	v_cvt_pk_bf16_f32 v106, v106, v107
	v_cvt_pk_bf16_f32 v107, v116, v117
	s_and_b64 vcc, exec, s[12:13]
	v_lshl_add_u64 v[108:109], v[112:113], 1, s[20:21]
	global_store_dwordx4 v[114:115], v[104:107], off
	s_cbranch_vccnz .LBB0_268
	v_and_b32_e32 v120, 64, v185
	v_xor_b32_e32 v116, 16, v185
	s_waitcnt lgkmcnt(0)
	v_add_u32_e32 v132, 64, v120
	v_and_b32_e32 v124, 0xffff, v104
	v_lshlrev_b32_e32 v131, 16, v106
	v_lshrrev_b32_e32 v125, 16, v104
	v_and_b32_e32 v128, 0xffff0000, v106
	v_and_b32_e32 v126, 0xffff, v105
	v_lshlrev_b32_e32 v129, 16, v107
	v_lshrrev_b32_e32 v127, 16, v105
	v_and_b32_e32 v130, 0xffff0000, v107
	v_cmp_lt_i32_e32 vcc, v116, v132
	v_or_b32_e32 v118, v131, v124
	v_or_b32_e32 v133, v128, v125
	v_or_b32_e32 v117, v129, v126
	v_or_b32_e32 v111, v130, v127
	v_cndmask_b32_e32 v116, v185, v116, vcc
	v_cndmask_b32_e64 v110, v118, v117, s[2:3]
	v_cndmask_b32_e64 v119, v133, v111, s[2:3]
	v_lshlrev_b32_e32 v120, 2, v116
	ds_bpermute_b32 v116, v120, v110
	ds_bpermute_b32 v134, v120, v119
	s_lshr_b32 s36, s33, 1
	v_lshl_add_u64 v[120:121], v[108:109], 0, s[36:37]
	v_lshl_add_u64 v[120:121], v[120:121], 0, v[152:153]
	s_waitcnt lgkmcnt(0)
	v_cndmask_b32_e64 v232, v118, v116, s[4:5]
	v_cndmask_b32_e64 v233, v116, v117, s[4:5]
	v_cndmask_b32_e64 v234, v133, v134, s[4:5]
	v_cndmask_b32_e64 v235, v134, v111, s[4:5]
	v_mov_b32_e32 v240, 0x2000
	v_mov_b32_e32 v241, 0
	v_cndmask_b32_e64 v240, 0, v240, s[4:5]
	v_lshl_add_u64 v[236:237], v[120:121], 0, v[240:241]
	global_store_dwordx2 v[236:237], v[232:233], off
	v_mov_b32_e32 v240, 0x1000
	v_lshl_add_u64 v[238:239], v[236:237], 0, v[240:241]
	global_store_dwordx2 v[238:239], v[234:235], off
	v_cndmask_b32_e64 v104, v104, v106, s[6:7]
	v_xor_b32_e32 v106, 32, v185
	v_cmp_lt_i32_e32 vcc, v106, v132
	v_cndmask_b32_e64 v105, v105, v107, s[6:7]
	s_lshr_b32 s36, s33, 3
	v_cndmask_b32_e32 v106, v185, v106, vcc
	v_lshlrev_b32_e32 v106, 2, v106
	ds_bpermute_b32 v117, v106, v104
	ds_bpermute_b32 v116, v106, v105
	v_lshl_add_u64 v[104:105], v[112:113], 1, v[156:157]
	v_lshl_add_u64 v[104:105], v[104:105], 0, s[36:37]
	s_waitcnt lgkmcnt(0)
	v_and_or_b32 v232, v117, s62, v131
	v_or_b32_sdwa v233, v117, v128 dst_sel:DWORD dst_unused:UNUSED_PAD src0_sel:WORD_1 src1_sel:DWORD
	v_and_or_b32 v234, v116, s62, v129
	v_or_b32_sdwa v235, v116, v130 dst_sel:DWORD dst_unused:UNUSED_PAD src0_sel:WORD_1 src1_sel:DWORD
	v_lshl_or_b32 v236, v117, 16, v124
	v_and_or_b32 v237, v117, s63, v125
	v_lshl_or_b32 v238, v116, 16, v126
	v_and_or_b32 v239, v116, s63, v127
	v_mov_b32_e32 v240, 0x1000
	v_mov_b32_e32 v241, 0
	v_cndmask_b32_e64 v232, v236, v232, s[8:9]
	v_cndmask_b32_e64 v233, v237, v233, s[8:9]
	v_cndmask_b32_e64 v234, v238, v234, s[8:9]
	v_cndmask_b32_e64 v235, v239, v235, s[8:9]
	v_cndmask_b32_e64 v240, 0, v240, s[8:9]
	v_lshl_add_u64 v[104:105], v[104:105], 0, v[240:241]
	global_store_dword v[104:105], v232, off
	global_store_dword v[104:105], v233, off offset:1024
	global_store_dword v[104:105], v234, off offset:2048
	global_store_dword v[104:105], v235, off offset:3072
.LBB0_268:
	v_pk_mul_f32 v[102:103], v[102:103], v[46:47]
	v_pk_mul_f32 v[100:101], v[100:101], v[44:45]
	v_pk_mul_f32 v[104:105], v[98:99], v[42:43]
	v_pk_mul_f32 v[98:99], v[96:97], v[40:41]
	v_cvt_pk_bf16_f32 v96, v100, v101
	v_cvt_pk_bf16_f32 v97, v102, v103
	v_cvt_pk_bf16_f32 v98, v98, v99
	v_cvt_pk_bf16_f32 v99, v104, v105
	s_and_b64 vcc, exec, s[12:13]
	global_store_dwordx4 v[114:115], v[96:99], off offset:256
	s_cbranch_vccnz .LBB0_278
	v_and_b32_e32 v106, 64, v185
	v_xor_b32_e32 v102, 16, v185
	v_add_u32_e32 v120, 64, v106
	v_and_b32_e32 v110, 0xffff, v96
	s_waitcnt lgkmcnt(1)
	v_lshlrev_b32_e32 v119, 16, v98
	v_lshrrev_b32_e32 v111, 16, v96
	s_waitcnt lgkmcnt(0)
	v_and_b32_e32 v116, 0xffff0000, v98
	v_and_b32_e32 v114, 0xffff, v97
	v_lshlrev_b32_e32 v117, 16, v99
	v_lshrrev_b32_e32 v115, 16, v97
	v_and_b32_e32 v118, 0xffff0000, v99
	v_cmp_lt_i32_e32 vcc, v102, v120
	v_or_b32_e32 v104, v119, v110
	v_or_b32_e32 v122, v116, v111
	v_or_b32_e32 v103, v117, v114
	v_or_b32_e32 v101, v118, v115
	v_cndmask_b32_e32 v102, v185, v102, vcc
	v_cndmask_b32_e64 v100, v104, v103, s[2:3]
	v_cndmask_b32_e64 v105, v122, v101, s[2:3]
	v_lshlrev_b32_e32 v106, 2, v102
	ds_bpermute_b32 v102, v106, v100
	ds_bpermute_b32 v121, v106, v105
	s_or_b32 s34, s33, 0x80
	s_lshr_b32 s36, s34, 1
	v_lshl_add_u64 v[106:107], v[108:109], 0, s[36:37]
	v_lshl_add_u64 v[106:107], v[106:107], 0, v[152:153]
	s_waitcnt lgkmcnt(0)
	v_cndmask_b32_e64 v232, v104, v102, s[4:5]
	v_cndmask_b32_e64 v233, v102, v103, s[4:5]
	v_cndmask_b32_e64 v234, v122, v121, s[4:5]
	v_cndmask_b32_e64 v235, v121, v101, s[4:5]
	v_mov_b32_e32 v240, 0x2000
	v_mov_b32_e32 v241, 0
	v_cndmask_b32_e64 v240, 0, v240, s[4:5]
	v_lshl_add_u64 v[236:237], v[106:107], 0, v[240:241]
	global_store_dwordx2 v[236:237], v[232:233], off
	v_mov_b32_e32 v240, 0x1000
	v_lshl_add_u64 v[238:239], v[236:237], 0, v[240:241]
	global_store_dwordx2 v[238:239], v[234:235], off
	v_cndmask_b32_e64 v96, v96, v98, s[6:7]
	v_xor_b32_e32 v98, 32, v185
	v_cmp_lt_i32_e32 vcc, v98, v120
	v_cndmask_b32_e64 v97, v97, v99, s[6:7]
	s_lshr_b32 s36, s34, 3
	v_cndmask_b32_e32 v98, v185, v98, vcc
	v_lshlrev_b32_e32 v98, 2, v98
	ds_bpermute_b32 v103, v98, v96
	ds_bpermute_b32 v102, v98, v97
	v_lshl_add_u64 v[96:97], v[112:113], 1, v[156:157]
	v_lshl_add_u64 v[96:97], v[96:97], 0, s[36:37]
	s_waitcnt lgkmcnt(0)
	v_and_or_b32 v232, v103, s62, v119
	v_or_b32_sdwa v233, v103, v116 dst_sel:DWORD dst_unused:UNUSED_PAD src0_sel:WORD_1 src1_sel:DWORD
	v_and_or_b32 v234, v102, s62, v117
	v_or_b32_sdwa v235, v102, v118 dst_sel:DWORD dst_unused:UNUSED_PAD src0_sel:WORD_1 src1_sel:DWORD
	v_lshl_or_b32 v236, v103, 16, v110
	v_and_or_b32 v237, v103, s63, v111
	v_lshl_or_b32 v238, v102, 16, v114
	v_and_or_b32 v239, v102, s63, v115
	v_mov_b32_e32 v240, 0x1000
	v_mov_b32_e32 v241, 0
	v_cndmask_b32_e64 v232, v236, v232, s[8:9]
	v_cndmask_b32_e64 v233, v237, v233, s[8:9]
	v_cndmask_b32_e64 v234, v238, v234, s[8:9]
	v_cndmask_b32_e64 v235, v239, v235, s[8:9]
	v_cndmask_b32_e64 v240, 0, v240, s[8:9]
	v_lshl_add_u64 v[96:97], v[96:97], 0, v[240:241]
	global_store_dword v[96:97], v232, off
	global_store_dword v[96:97], v233, off offset:1024
	global_store_dword v[96:97], v234, off offset:2048
	global_store_dword v[96:97], v235, off offset:3072
.LBB0_278:
	s_nop 0
	v_or_b32_e32 v98, 48, v186
	v_mov_b64_e32 v[96:97], s[28:29]
	v_mad_i64_i32 v[96:97], s[76:77], v98, s61, v[96:97]
	v_lshl_add_u64 v[98:99], v[168:169], 1, v[96:97]
	v_add_u32_e32 v100, 0xfffffe30, v186
	v_mov_b64_e32 v[96:97], s[74:75]
	v_mad_i64_i32 v[96:97], s[76:77], v100, s54, v[96:97]
	v_pk_mul_f32 v[94:95], v[94:95], v[54:55]
	v_pk_mul_f32 v[92:93], v[92:93], v[52:53]
	v_pk_mul_f32 v[100:101], v[90:91], v[50:51]
	v_pk_mul_f32 v[90:91], v[88:89], v[48:49]
	v_cvt_pk_bf16_f32 v88, v92, v93
	v_cvt_pk_bf16_f32 v89, v94, v95
	v_cvt_pk_bf16_f32 v90, v90, v91
	v_cvt_pk_bf16_f32 v91, v100, v101
	s_and_b64 vcc, exec, s[12:13]
	v_lshl_add_u64 v[92:93], v[96:97], 1, s[20:21]
	global_store_dwordx4 v[98:99], v[88:91], off
	s_cbranch_vccnz .LBB0_288
	v_and_b32_e32 v104, 64, v185
	v_xor_b32_e32 v100, 16, v185
	s_waitcnt lgkmcnt(0)
	v_add_u32_e32 v116, 64, v104
	v_and_b32_e32 v108, 0xffff, v88
	v_lshlrev_b32_e32 v115, 16, v90
	v_lshrrev_b32_e32 v109, 16, v88
	v_and_b32_e32 v112, 0xffff0000, v90
	v_and_b32_e32 v110, 0xffff, v89
	v_lshlrev_b32_e32 v113, 16, v91
	v_lshrrev_b32_e32 v111, 16, v89
	v_and_b32_e32 v114, 0xffff0000, v91
	v_cmp_lt_i32_e32 vcc, v100, v116
	v_or_b32_e32 v102, v115, v108
	v_or_b32_e32 v117, v112, v109
	v_or_b32_e32 v101, v113, v110
	v_or_b32_e32 v95, v114, v111
	v_cndmask_b32_e32 v100, v185, v100, vcc
	v_cndmask_b32_e64 v94, v102, v101, s[2:3]
	v_cndmask_b32_e64 v103, v117, v95, s[2:3]
	v_lshlrev_b32_e32 v104, 2, v100
	ds_bpermute_b32 v100, v104, v94
	ds_bpermute_b32 v118, v104, v103
	s_lshr_b32 s36, s33, 1
	v_lshl_add_u64 v[104:105], v[92:93], 0, s[36:37]
	v_lshl_add_u64 v[104:105], v[104:105], 0, v[152:153]
	s_waitcnt lgkmcnt(0)
	v_cndmask_b32_e64 v232, v102, v100, s[4:5]
	v_cndmask_b32_e64 v233, v100, v101, s[4:5]
	v_cndmask_b32_e64 v234, v117, v118, s[4:5]
	v_cndmask_b32_e64 v235, v118, v95, s[4:5]
	v_mov_b32_e32 v240, 0x2000
	v_mov_b32_e32 v241, 0
	v_cndmask_b32_e64 v240, 0, v240, s[4:5]
	v_lshl_add_u64 v[236:237], v[104:105], 0, v[240:241]
	global_store_dwordx2 v[236:237], v[232:233], off
	v_mov_b32_e32 v240, 0x1000
	v_lshl_add_u64 v[238:239], v[236:237], 0, v[240:241]
	global_store_dwordx2 v[238:239], v[234:235], off
	v_cndmask_b32_e64 v88, v88, v90, s[6:7]
	v_xor_b32_e32 v90, 32, v185
	v_cmp_lt_i32_e32 vcc, v90, v116
	v_cndmask_b32_e64 v89, v89, v91, s[6:7]
	s_lshr_b32 s36, s33, 3
	v_cndmask_b32_e32 v90, v185, v90, vcc
	v_lshlrev_b32_e32 v90, 2, v90
	ds_bpermute_b32 v101, v90, v88
	ds_bpermute_b32 v100, v90, v89
	v_lshl_add_u64 v[88:89], v[96:97], 1, v[156:157]
	v_lshl_add_u64 v[88:89], v[88:89], 0, s[36:37]
	s_waitcnt lgkmcnt(0)
	v_and_or_b32 v232, v101, s62, v115
	v_or_b32_sdwa v233, v101, v112 dst_sel:DWORD dst_unused:UNUSED_PAD src0_sel:WORD_1 src1_sel:DWORD
	v_and_or_b32 v234, v100, s62, v113
	v_or_b32_sdwa v235, v100, v114 dst_sel:DWORD dst_unused:UNUSED_PAD src0_sel:WORD_1 src1_sel:DWORD
	v_lshl_or_b32 v236, v101, 16, v108
	v_and_or_b32 v237, v101, s63, v109
	v_lshl_or_b32 v238, v100, 16, v110
	v_and_or_b32 v239, v100, s63, v111
	v_mov_b32_e32 v240, 0x1000
	v_mov_b32_e32 v241, 0
	v_cndmask_b32_e64 v232, v236, v232, s[8:9]
	v_cndmask_b32_e64 v233, v237, v233, s[8:9]
	v_cndmask_b32_e64 v234, v238, v234, s[8:9]
	v_cndmask_b32_e64 v235, v239, v235, s[8:9]
	v_cndmask_b32_e64 v240, 0, v240, s[8:9]
	v_lshl_add_u64 v[88:89], v[88:89], 0, v[240:241]
	global_store_dword v[88:89], v232, off
	global_store_dword v[88:89], v233, off offset:1024
	global_store_dword v[88:89], v234, off offset:2048
	global_store_dword v[88:89], v235, off offset:3072
.LBB0_288:
	v_pk_mul_f32 v[86:87], v[86:87], v[46:47]
	v_pk_mul_f32 v[84:85], v[84:85], v[44:45]
	v_pk_mul_f32 v[88:89], v[82:83], v[42:43]
	v_pk_mul_f32 v[82:83], v[80:81], v[40:41]
	v_cvt_pk_bf16_f32 v80, v84, v85
	v_cvt_pk_bf16_f32 v81, v86, v87
	v_cvt_pk_bf16_f32 v82, v82, v83
	v_cvt_pk_bf16_f32 v83, v88, v89
	s_and_b64 vcc, exec, s[12:13]
	global_store_dwordx4 v[98:99], v[80:83], off offset:256
	s_cbranch_vccnz .LBB0_298
	v_and_b32_e32 v90, 64, v185
	v_xor_b32_e32 v86, 16, v185
	v_add_u32_e32 v104, 64, v90
	v_and_b32_e32 v94, 0xffff, v80
	s_waitcnt lgkmcnt(1)
	v_lshlrev_b32_e32 v103, 16, v82
	v_lshrrev_b32_e32 v95, 16, v80
	s_waitcnt lgkmcnt(0)
	v_and_b32_e32 v100, 0xffff0000, v82
	v_and_b32_e32 v98, 0xffff, v81
	v_lshlrev_b32_e32 v101, 16, v83
	v_lshrrev_b32_e32 v99, 16, v81
	v_and_b32_e32 v102, 0xffff0000, v83
	v_cmp_lt_i32_e32 vcc, v86, v104
	v_or_b32_e32 v88, v103, v94
	v_or_b32_e32 v106, v100, v95
	v_or_b32_e32 v87, v101, v98
	v_or_b32_e32 v85, v102, v99
	v_cndmask_b32_e32 v86, v185, v86, vcc
	v_cndmask_b32_e64 v84, v88, v87, s[2:3]
	v_cndmask_b32_e64 v89, v106, v85, s[2:3]
	v_lshlrev_b32_e32 v90, 2, v86
	ds_bpermute_b32 v86, v90, v84
	ds_bpermute_b32 v105, v90, v89
	s_or_b32 s34, s33, 0x80
	s_lshr_b32 s36, s34, 1
	v_lshl_add_u64 v[90:91], v[92:93], 0, s[36:37]
	v_lshl_add_u64 v[90:91], v[90:91], 0, v[152:153]
	s_waitcnt lgkmcnt(0)
	v_cndmask_b32_e64 v232, v88, v86, s[4:5]
	v_cndmask_b32_e64 v233, v86, v87, s[4:5]
	v_cndmask_b32_e64 v234, v106, v105, s[4:5]
	v_cndmask_b32_e64 v235, v105, v85, s[4:5]
	v_mov_b32_e32 v240, 0x2000
	v_mov_b32_e32 v241, 0
	v_cndmask_b32_e64 v240, 0, v240, s[4:5]
	v_lshl_add_u64 v[236:237], v[90:91], 0, v[240:241]
	global_store_dwordx2 v[236:237], v[232:233], off
	v_mov_b32_e32 v240, 0x1000
	v_lshl_add_u64 v[238:239], v[236:237], 0, v[240:241]
	global_store_dwordx2 v[238:239], v[234:235], off
	v_cndmask_b32_e64 v80, v80, v82, s[6:7]
	v_xor_b32_e32 v82, 32, v185
	v_cmp_lt_i32_e32 vcc, v82, v104
	v_cndmask_b32_e64 v81, v81, v83, s[6:7]
	s_lshr_b32 s36, s34, 3
	v_cndmask_b32_e32 v82, v185, v82, vcc
	v_lshlrev_b32_e32 v82, 2, v82
	ds_bpermute_b32 v87, v82, v80
	ds_bpermute_b32 v86, v82, v81
	v_lshl_add_u64 v[80:81], v[96:97], 1, v[156:157]
	v_lshl_add_u64 v[80:81], v[80:81], 0, s[36:37]
	s_waitcnt lgkmcnt(0)
	v_and_or_b32 v232, v87, s62, v103
	v_or_b32_sdwa v233, v87, v100 dst_sel:DWORD dst_unused:UNUSED_PAD src0_sel:WORD_1 src1_sel:DWORD
	v_and_or_b32 v234, v86, s62, v101
	v_or_b32_sdwa v235, v86, v102 dst_sel:DWORD dst_unused:UNUSED_PAD src0_sel:WORD_1 src1_sel:DWORD
	v_lshl_or_b32 v236, v87, 16, v94
	v_and_or_b32 v237, v87, s63, v95
	v_lshl_or_b32 v238, v86, 16, v98
	v_and_or_b32 v239, v86, s63, v99
	v_mov_b32_e32 v240, 0x1000
	v_mov_b32_e32 v241, 0
	v_cndmask_b32_e64 v232, v236, v232, s[8:9]
	v_cndmask_b32_e64 v233, v237, v233, s[8:9]
	v_cndmask_b32_e64 v234, v238, v234, s[8:9]
	v_cndmask_b32_e64 v235, v239, v235, s[8:9]
	v_cndmask_b32_e64 v240, 0, v240, s[8:9]
	v_lshl_add_u64 v[80:81], v[80:81], 0, v[240:241]
	global_store_dword v[80:81], v232, off
	global_store_dword v[80:81], v233, off offset:1024
	global_store_dword v[80:81], v234, off offset:2048
	global_store_dword v[80:81], v235, off offset:3072
.LBB0_298:
	s_nop 0
	v_add_u32_e32 v82, 0x80, v186
	v_mov_b64_e32 v[80:81], s[28:29]
	v_mad_i64_i32 v[80:81], s[76:77], v82, s61, v[80:81]
	v_lshl_add_u64 v[82:83], v[168:169], 1, v[80:81]
	v_add_u32_e32 v84, 0xfffffe80, v186
	v_mov_b64_e32 v[80:81], s[74:75]
	v_mad_i64_i32 v[80:81], s[76:77], v84, s54, v[80:81]
	v_pk_mul_f32 v[78:79], v[78:79], v[54:55]
	v_pk_mul_f32 v[76:77], v[76:77], v[52:53]
	v_pk_mul_f32 v[84:85], v[74:75], v[50:51]
	v_pk_mul_f32 v[74:75], v[72:73], v[48:49]
	v_cvt_pk_bf16_f32 v72, v76, v77
	v_cvt_pk_bf16_f32 v73, v78, v79
	v_cvt_pk_bf16_f32 v74, v74, v75
	v_cvt_pk_bf16_f32 v75, v84, v85
	s_and_b64 vcc, exec, s[12:13]
	v_lshl_add_u64 v[76:77], v[80:81], 1, s[20:21]
	global_store_dwordx4 v[82:83], v[72:75], off
	s_cbranch_vccnz .LBB0_308
	v_and_b32_e32 v88, 64, v185
	v_xor_b32_e32 v84, 16, v185
	s_waitcnt lgkmcnt(0)
	v_add_u32_e32 v100, 64, v88
	v_and_b32_e32 v92, 0xffff, v72
	v_lshlrev_b32_e32 v99, 16, v74
	v_lshrrev_b32_e32 v93, 16, v72
	v_and_b32_e32 v96, 0xffff0000, v74
	v_and_b32_e32 v94, 0xffff, v73
	v_lshlrev_b32_e32 v97, 16, v75
	v_lshrrev_b32_e32 v95, 16, v73
	v_and_b32_e32 v98, 0xffff0000, v75
	v_cmp_lt_i32_e32 vcc, v84, v100
	v_or_b32_e32 v86, v99, v92
	v_or_b32_e32 v101, v96, v93
	v_or_b32_e32 v85, v97, v94
	v_or_b32_e32 v79, v98, v95
	v_cndmask_b32_e32 v84, v185, v84, vcc
	v_cndmask_b32_e64 v78, v86, v85, s[2:3]
	v_cndmask_b32_e64 v87, v101, v79, s[2:3]
	v_lshlrev_b32_e32 v88, 2, v84
	ds_bpermute_b32 v84, v88, v78
	ds_bpermute_b32 v102, v88, v87
	s_lshr_b32 s36, s33, 1
	v_lshl_add_u64 v[88:89], v[76:77], 0, s[36:37]
	v_lshl_add_u64 v[88:89], v[88:89], 0, v[152:153]
	s_waitcnt lgkmcnt(0)
	v_cndmask_b32_e64 v232, v86, v84, s[4:5]
	v_cndmask_b32_e64 v233, v84, v85, s[4:5]
	v_cndmask_b32_e64 v234, v101, v102, s[4:5]
	v_cndmask_b32_e64 v235, v102, v79, s[4:5]
	v_mov_b32_e32 v240, 0x2000
	v_mov_b32_e32 v241, 0
	v_cndmask_b32_e64 v240, 0, v240, s[4:5]
	v_lshl_add_u64 v[236:237], v[88:89], 0, v[240:241]
	global_store_dwordx2 v[236:237], v[232:233], off
	v_mov_b32_e32 v240, 0x1000
	v_lshl_add_u64 v[238:239], v[236:237], 0, v[240:241]
	global_store_dwordx2 v[238:239], v[234:235], off
	v_cndmask_b32_e64 v72, v72, v74, s[6:7]
	v_xor_b32_e32 v74, 32, v185
	v_cmp_lt_i32_e32 vcc, v74, v100
	v_cndmask_b32_e64 v73, v73, v75, s[6:7]
	s_lshr_b32 s36, s33, 3
	v_cndmask_b32_e32 v74, v185, v74, vcc
	v_lshlrev_b32_e32 v74, 2, v74
	ds_bpermute_b32 v85, v74, v72
	ds_bpermute_b32 v84, v74, v73
	v_lshl_add_u64 v[72:73], v[80:81], 1, v[156:157]
	v_lshl_add_u64 v[72:73], v[72:73], 0, s[36:37]
	s_waitcnt lgkmcnt(0)
	v_and_or_b32 v232, v85, s62, v99
	v_or_b32_sdwa v233, v85, v96 dst_sel:DWORD dst_unused:UNUSED_PAD src0_sel:WORD_1 src1_sel:DWORD
	v_and_or_b32 v234, v84, s62, v97
	v_or_b32_sdwa v235, v84, v98 dst_sel:DWORD dst_unused:UNUSED_PAD src0_sel:WORD_1 src1_sel:DWORD
	v_lshl_or_b32 v236, v85, 16, v92
	v_and_or_b32 v237, v85, s63, v93
	v_lshl_or_b32 v238, v84, 16, v94
	v_and_or_b32 v239, v84, s63, v95
	v_mov_b32_e32 v240, 0x1000
	v_mov_b32_e32 v241, 0
	v_cndmask_b32_e64 v232, v236, v232, s[8:9]
	v_cndmask_b32_e64 v233, v237, v233, s[8:9]
	v_cndmask_b32_e64 v234, v238, v234, s[8:9]
	v_cndmask_b32_e64 v235, v239, v235, s[8:9]
	v_cndmask_b32_e64 v240, 0, v240, s[8:9]
	v_lshl_add_u64 v[72:73], v[72:73], 0, v[240:241]
	global_store_dword v[72:73], v232, off
	global_store_dword v[72:73], v233, off offset:1024
	global_store_dword v[72:73], v234, off offset:2048
	global_store_dword v[72:73], v235, off offset:3072
.LBB0_308:
	v_pk_mul_f32 v[70:71], v[70:71], v[46:47]
	v_pk_mul_f32 v[68:69], v[68:69], v[44:45]
	v_pk_mul_f32 v[72:73], v[66:67], v[42:43]
	v_pk_mul_f32 v[66:67], v[64:65], v[40:41]
	v_cvt_pk_bf16_f32 v64, v68, v69
	v_cvt_pk_bf16_f32 v65, v70, v71
	v_cvt_pk_bf16_f32 v66, v66, v67
	v_cvt_pk_bf16_f32 v67, v72, v73
	s_and_b64 vcc, exec, s[12:13]
	global_store_dwordx4 v[82:83], v[64:67], off offset:256
	s_cbranch_vccnz .LBB0_318
	v_and_b32_e32 v74, 64, v185
	v_xor_b32_e32 v70, 16, v185
	v_add_u32_e32 v88, 64, v74
	v_and_b32_e32 v78, 0xffff, v64
	s_waitcnt lgkmcnt(1)
	v_lshlrev_b32_e32 v87, 16, v66
	v_lshrrev_b32_e32 v79, 16, v64
	s_waitcnt lgkmcnt(0)
	v_and_b32_e32 v84, 0xffff0000, v66
	v_and_b32_e32 v82, 0xffff, v65
	v_lshlrev_b32_e32 v85, 16, v67
	v_lshrrev_b32_e32 v83, 16, v65
	v_and_b32_e32 v86, 0xffff0000, v67
	v_cmp_lt_i32_e32 vcc, v70, v88
	v_or_b32_e32 v72, v87, v78
	v_or_b32_e32 v90, v84, v79
	v_or_b32_e32 v71, v85, v82
	v_or_b32_e32 v69, v86, v83
	v_cndmask_b32_e32 v70, v185, v70, vcc
	v_cndmask_b32_e64 v68, v72, v71, s[2:3]
	v_cndmask_b32_e64 v73, v90, v69, s[2:3]
	v_lshlrev_b32_e32 v74, 2, v70
	ds_bpermute_b32 v70, v74, v68
	ds_bpermute_b32 v89, v74, v73
	s_or_b32 s34, s33, 0x80
	s_lshr_b32 s36, s34, 1
	v_lshl_add_u64 v[74:75], v[76:77], 0, s[36:37]
	v_lshl_add_u64 v[74:75], v[74:75], 0, v[152:153]
	s_waitcnt lgkmcnt(0)
	v_cndmask_b32_e64 v232, v72, v70, s[4:5]
	v_cndmask_b32_e64 v233, v70, v71, s[4:5]
	v_cndmask_b32_e64 v234, v90, v89, s[4:5]
	v_cndmask_b32_e64 v235, v89, v69, s[4:5]
	v_mov_b32_e32 v240, 0x2000
	v_mov_b32_e32 v241, 0
	v_cndmask_b32_e64 v240, 0, v240, s[4:5]
	v_lshl_add_u64 v[236:237], v[74:75], 0, v[240:241]
	global_store_dwordx2 v[236:237], v[232:233], off
	v_mov_b32_e32 v240, 0x1000
	v_lshl_add_u64 v[238:239], v[236:237], 0, v[240:241]
	global_store_dwordx2 v[238:239], v[234:235], off
	v_cndmask_b32_e64 v64, v64, v66, s[6:7]
	v_xor_b32_e32 v66, 32, v185
	v_cmp_lt_i32_e32 vcc, v66, v88
	v_cndmask_b32_e64 v65, v65, v67, s[6:7]
	s_lshr_b32 s36, s34, 3
	v_cndmask_b32_e32 v66, v185, v66, vcc
	v_lshlrev_b32_e32 v66, 2, v66
	ds_bpermute_b32 v71, v66, v64
	ds_bpermute_b32 v70, v66, v65
	v_lshl_add_u64 v[64:65], v[80:81], 1, v[156:157]
	v_lshl_add_u64 v[64:65], v[64:65], 0, s[36:37]
	s_waitcnt lgkmcnt(0)
	v_and_or_b32 v232, v71, s62, v87
	v_or_b32_sdwa v233, v71, v84 dst_sel:DWORD dst_unused:UNUSED_PAD src0_sel:WORD_1 src1_sel:DWORD
	v_and_or_b32 v234, v70, s62, v85
	v_or_b32_sdwa v235, v70, v86 dst_sel:DWORD dst_unused:UNUSED_PAD src0_sel:WORD_1 src1_sel:DWORD
	v_lshl_or_b32 v236, v71, 16, v78
	v_and_or_b32 v237, v71, s63, v79
	v_lshl_or_b32 v238, v70, 16, v82
	v_and_or_b32 v239, v70, s63, v83
	v_mov_b32_e32 v240, 0x1000
	v_mov_b32_e32 v241, 0
	v_cndmask_b32_e64 v232, v236, v232, s[8:9]
	v_cndmask_b32_e64 v233, v237, v233, s[8:9]
	v_cndmask_b32_e64 v234, v238, v234, s[8:9]
	v_cndmask_b32_e64 v235, v239, v235, s[8:9]
	v_cndmask_b32_e64 v240, 0, v240, s[8:9]
	v_lshl_add_u64 v[64:65], v[64:65], 0, v[240:241]
	global_store_dword v[64:65], v232, off
	global_store_dword v[64:65], v233, off offset:1024
	global_store_dword v[64:65], v234, off offset:2048
	global_store_dword v[64:65], v235, off offset:3072
.LBB0_318:
	s_nop 0
	v_add_u32_e32 v66, 0x90, v186
	v_mov_b64_e32 v[64:65], s[28:29]
	v_mad_i64_i32 v[64:65], s[76:77], v66, s61, v[64:65]
	v_lshl_add_u64 v[66:67], v[168:169], 1, v[64:65]
	v_add_u32_e32 v68, 0xfffffe90, v186
	v_mov_b64_e32 v[64:65], s[74:75]
	v_mad_i64_i32 v[64:65], s[76:77], v68, s54, v[64:65]
	v_pk_mul_f32 v[62:63], v[62:63], v[54:55]
	v_pk_mul_f32 v[60:61], v[60:61], v[52:53]
	v_pk_mul_f32 v[68:69], v[58:59], v[50:51]
	v_pk_mul_f32 v[58:59], v[56:57], v[48:49]
	v_cvt_pk_bf16_f32 v56, v60, v61
	v_cvt_pk_bf16_f32 v57, v62, v63
	v_cvt_pk_bf16_f32 v58, v58, v59
	v_cvt_pk_bf16_f32 v59, v68, v69
	s_and_b64 vcc, exec, s[12:13]
	v_lshl_add_u64 v[60:61], v[64:65], 1, s[20:21]
	global_store_dwordx4 v[66:67], v[56:59], off
	s_cbranch_vccnz .LBB0_328
	v_and_b32_e32 v72, 64, v185
	v_xor_b32_e32 v68, 16, v185
	s_waitcnt lgkmcnt(0)
	v_add_u32_e32 v84, 64, v72
	v_and_b32_e32 v76, 0xffff, v56
	v_lshlrev_b32_e32 v83, 16, v58
	v_lshrrev_b32_e32 v77, 16, v56
	v_and_b32_e32 v80, 0xffff0000, v58
	v_and_b32_e32 v78, 0xffff, v57
	v_lshlrev_b32_e32 v81, 16, v59
	v_lshrrev_b32_e32 v79, 16, v57
	v_and_b32_e32 v82, 0xffff0000, v59
	v_cmp_lt_i32_e32 vcc, v68, v84
	v_or_b32_e32 v70, v83, v76
	v_or_b32_e32 v85, v80, v77
	v_or_b32_e32 v69, v81, v78
	v_or_b32_e32 v63, v82, v79
	v_cndmask_b32_e32 v68, v185, v68, vcc
	v_cndmask_b32_e64 v62, v70, v69, s[2:3]
	v_cndmask_b32_e64 v71, v85, v63, s[2:3]
	v_lshlrev_b32_e32 v72, 2, v68
	ds_bpermute_b32 v68, v72, v62
	ds_bpermute_b32 v86, v72, v71
	s_lshr_b32 s36, s33, 1
	v_lshl_add_u64 v[72:73], v[60:61], 0, s[36:37]
	v_lshl_add_u64 v[72:73], v[72:73], 0, v[152:153]
	s_waitcnt lgkmcnt(0)
	v_cndmask_b32_e64 v232, v70, v68, s[4:5]
	v_cndmask_b32_e64 v233, v68, v69, s[4:5]
	v_cndmask_b32_e64 v234, v85, v86, s[4:5]
	v_cndmask_b32_e64 v235, v86, v63, s[4:5]
	v_mov_b32_e32 v240, 0x2000
	v_mov_b32_e32 v241, 0
	v_cndmask_b32_e64 v240, 0, v240, s[4:5]
	v_lshl_add_u64 v[236:237], v[72:73], 0, v[240:241]
	global_store_dwordx2 v[236:237], v[232:233], off
	v_mov_b32_e32 v240, 0x1000
	v_lshl_add_u64 v[238:239], v[236:237], 0, v[240:241]
	global_store_dwordx2 v[238:239], v[234:235], off
	v_cndmask_b32_e64 v56, v56, v58, s[6:7]
	v_xor_b32_e32 v58, 32, v185
	v_cmp_lt_i32_e32 vcc, v58, v84
	v_cndmask_b32_e64 v57, v57, v59, s[6:7]
	s_lshr_b32 s36, s33, 3
	v_cndmask_b32_e32 v58, v185, v58, vcc
	v_lshlrev_b32_e32 v58, 2, v58
	ds_bpermute_b32 v69, v58, v56
	ds_bpermute_b32 v68, v58, v57
	v_lshl_add_u64 v[56:57], v[64:65], 1, v[156:157]
	v_lshl_add_u64 v[56:57], v[56:57], 0, s[36:37]
	s_waitcnt lgkmcnt(0)
	v_and_or_b32 v232, v69, s62, v83
	v_or_b32_sdwa v233, v69, v80 dst_sel:DWORD dst_unused:UNUSED_PAD src0_sel:WORD_1 src1_sel:DWORD
	v_and_or_b32 v234, v68, s62, v81
	v_or_b32_sdwa v235, v68, v82 dst_sel:DWORD dst_unused:UNUSED_PAD src0_sel:WORD_1 src1_sel:DWORD
	v_lshl_or_b32 v236, v69, 16, v76
	v_and_or_b32 v237, v69, s63, v77
	v_lshl_or_b32 v238, v68, 16, v78
	v_and_or_b32 v239, v68, s63, v79
	v_mov_b32_e32 v240, 0x1000
	v_mov_b32_e32 v241, 0
	v_cndmask_b32_e64 v232, v236, v232, s[8:9]
	v_cndmask_b32_e64 v233, v237, v233, s[8:9]
	v_cndmask_b32_e64 v234, v238, v234, s[8:9]
	v_cndmask_b32_e64 v235, v239, v235, s[8:9]
	v_cndmask_b32_e64 v240, 0, v240, s[8:9]
	v_lshl_add_u64 v[56:57], v[56:57], 0, v[240:241]
	global_store_dword v[56:57], v232, off
	global_store_dword v[56:57], v233, off offset:1024
	global_store_dword v[56:57], v234, off offset:2048
	global_store_dword v[56:57], v235, off offset:3072
.LBB0_328:
	v_pk_mul_f32 v[38:39], v[38:39], v[46:47]
	v_pk_mul_f32 v[36:37], v[36:37], v[44:45]
	v_pk_mul_f32 v[56:57], v[34:35], v[42:43]
	v_pk_mul_f32 v[34:35], v[32:33], v[40:41]
	v_cvt_pk_bf16_f32 v32, v36, v37
	v_cvt_pk_bf16_f32 v33, v38, v39
	v_cvt_pk_bf16_f32 v34, v34, v35
	v_cvt_pk_bf16_f32 v35, v56, v57
	s_and_b64 vcc, exec, s[12:13]
	global_store_dwordx4 v[66:67], v[32:35], off offset:256
	s_cbranch_vccnz .LBB0_338
	v_and_b32_e32 v58, 64, v185
	v_xor_b32_e32 v38, 16, v185
	v_add_u32_e32 v72, 64, v58
	v_and_b32_e32 v62, 0xffff, v32
	s_waitcnt lgkmcnt(1)
	v_lshlrev_b32_e32 v71, 16, v34
	v_lshrrev_b32_e32 v63, 16, v32
	s_waitcnt lgkmcnt(0)
	v_and_b32_e32 v68, 0xffff0000, v34
	v_and_b32_e32 v66, 0xffff, v33
	v_lshlrev_b32_e32 v69, 16, v35
	v_lshrrev_b32_e32 v67, 16, v33
	v_and_b32_e32 v70, 0xffff0000, v35
	v_cmp_lt_i32_e32 vcc, v38, v72
	v_or_b32_e32 v56, v71, v62
	v_or_b32_e32 v74, v68, v63
	v_or_b32_e32 v39, v69, v66
	v_or_b32_e32 v37, v70, v67
	v_cndmask_b32_e32 v38, v185, v38, vcc
	v_cndmask_b32_e64 v36, v56, v39, s[2:3]
	v_cndmask_b32_e64 v57, v74, v37, s[2:3]
	v_lshlrev_b32_e32 v58, 2, v38
	ds_bpermute_b32 v38, v58, v36
	ds_bpermute_b32 v73, v58, v57
	s_or_b32 s34, s33, 0x80
	s_lshr_b32 s36, s34, 1
	v_lshl_add_u64 v[58:59], v[60:61], 0, s[36:37]
	v_lshl_add_u64 v[58:59], v[58:59], 0, v[152:153]
	s_waitcnt lgkmcnt(0)
	v_cndmask_b32_e64 v232, v56, v38, s[4:5]
	v_cndmask_b32_e64 v233, v38, v39, s[4:5]
	v_cndmask_b32_e64 v234, v74, v73, s[4:5]
	v_cndmask_b32_e64 v235, v73, v37, s[4:5]
	v_mov_b32_e32 v240, 0x2000
	v_mov_b32_e32 v241, 0
	v_cndmask_b32_e64 v240, 0, v240, s[4:5]
	v_lshl_add_u64 v[236:237], v[58:59], 0, v[240:241]
	global_store_dwordx2 v[236:237], v[232:233], off
	v_mov_b32_e32 v240, 0x1000
	v_lshl_add_u64 v[238:239], v[236:237], 0, v[240:241]
	global_store_dwordx2 v[238:239], v[234:235], off
	v_cndmask_b32_e64 v32, v32, v34, s[6:7]
	v_xor_b32_e32 v34, 32, v185
	v_cmp_lt_i32_e32 vcc, v34, v72
	v_cndmask_b32_e64 v33, v33, v35, s[6:7]
	s_lshr_b32 s36, s34, 3
	v_cndmask_b32_e32 v34, v185, v34, vcc
	v_lshlrev_b32_e32 v34, 2, v34
	ds_bpermute_b32 v39, v34, v32
	ds_bpermute_b32 v38, v34, v33
	v_lshl_add_u64 v[32:33], v[64:65], 1, v[156:157]
	v_lshl_add_u64 v[32:33], v[32:33], 0, s[36:37]
	s_waitcnt lgkmcnt(0)
	v_and_or_b32 v232, v39, s62, v71
	v_or_b32_sdwa v233, v39, v68 dst_sel:DWORD dst_unused:UNUSED_PAD src0_sel:WORD_1 src1_sel:DWORD
	v_and_or_b32 v234, v38, s62, v69
	v_or_b32_sdwa v235, v38, v70 dst_sel:DWORD dst_unused:UNUSED_PAD src0_sel:WORD_1 src1_sel:DWORD
	v_lshl_or_b32 v236, v39, 16, v62
	v_and_or_b32 v237, v39, s63, v63
	v_lshl_or_b32 v238, v38, 16, v66
	v_and_or_b32 v239, v38, s63, v67
	v_mov_b32_e32 v240, 0x1000
	v_mov_b32_e32 v241, 0
	v_cndmask_b32_e64 v232, v236, v232, s[8:9]
	v_cndmask_b32_e64 v233, v237, v233, s[8:9]
	v_cndmask_b32_e64 v234, v238, v234, s[8:9]
	v_cndmask_b32_e64 v235, v239, v235, s[8:9]
	v_cndmask_b32_e64 v240, 0, v240, s[8:9]
	v_lshl_add_u64 v[32:33], v[32:33], 0, v[240:241]
	global_store_dword v[32:33], v232, off
	global_store_dword v[32:33], v233, off offset:1024
	global_store_dword v[32:33], v234, off offset:2048
	global_store_dword v[32:33], v235, off offset:3072
.LBB0_338:
	s_nop 0
	v_add_u32_e32 v34, 0xa0, v186
	v_mov_b64_e32 v[32:33], s[28:29]
	v_mad_i64_i32 v[32:33], s[76:77], v34, s61, v[32:33]
	v_lshl_add_u64 v[34:35], v[168:169], 1, v[32:33]
	v_add_u32_e32 v36, 0xfffffea0, v186
	v_mov_b64_e32 v[32:33], s[74:75]
	v_mad_i64_i32 v[32:33], s[76:77], v36, s54, v[32:33]
	v_pk_mul_f32 v[30:31], v[30:31], v[54:55]
	v_pk_mul_f32 v[28:29], v[28:29], v[52:53]
	v_pk_mul_f32 v[36:37], v[26:27], v[50:51]
	v_pk_mul_f32 v[26:27], v[24:25], v[48:49]
	v_cvt_pk_bf16_f32 v24, v28, v29
	v_cvt_pk_bf16_f32 v25, v30, v31
	v_cvt_pk_bf16_f32 v26, v26, v27
	v_cvt_pk_bf16_f32 v27, v36, v37
	s_and_b64 vcc, exec, s[12:13]
	v_lshl_add_u64 v[28:29], v[32:33], 1, s[20:21]
	global_store_dwordx4 v[34:35], v[24:27], off
	s_cbranch_vccnz .LBB0_348
	v_and_b32_e32 v56, 64, v185
	v_xor_b32_e32 v36, 16, v185
	s_waitcnt lgkmcnt(0)
	v_add_u32_e32 v68, 64, v56
	v_and_b32_e32 v60, 0xffff, v24
	v_lshlrev_b32_e32 v67, 16, v26
	v_lshrrev_b32_e32 v61, 16, v24
	v_and_b32_e32 v64, 0xffff0000, v26
	v_and_b32_e32 v62, 0xffff, v25
	v_lshlrev_b32_e32 v65, 16, v27
	v_lshrrev_b32_e32 v63, 16, v25
	v_and_b32_e32 v66, 0xffff0000, v27
	v_cmp_lt_i32_e32 vcc, v36, v68
	v_or_b32_e32 v38, v67, v60
	v_or_b32_e32 v69, v64, v61
	v_or_b32_e32 v37, v65, v62
	v_or_b32_e32 v31, v66, v63
	v_cndmask_b32_e32 v36, v185, v36, vcc
	v_cndmask_b32_e64 v30, v38, v37, s[2:3]
	v_cndmask_b32_e64 v39, v69, v31, s[2:3]
	v_lshlrev_b32_e32 v56, 2, v36
	ds_bpermute_b32 v36, v56, v30
	ds_bpermute_b32 v70, v56, v39
	s_lshr_b32 s36, s33, 1
	v_lshl_add_u64 v[56:57], v[28:29], 0, s[36:37]
	v_lshl_add_u64 v[56:57], v[56:57], 0, v[152:153]
	s_waitcnt lgkmcnt(0)
	v_cndmask_b32_e64 v232, v38, v36, s[4:5]
	v_cndmask_b32_e64 v233, v36, v37, s[4:5]
	v_cndmask_b32_e64 v234, v69, v70, s[4:5]
	v_cndmask_b32_e64 v235, v70, v31, s[4:5]
	v_mov_b32_e32 v240, 0x2000
	v_mov_b32_e32 v241, 0
	v_cndmask_b32_e64 v240, 0, v240, s[4:5]
	v_lshl_add_u64 v[236:237], v[56:57], 0, v[240:241]
	global_store_dwordx2 v[236:237], v[232:233], off
	v_mov_b32_e32 v240, 0x1000
	v_lshl_add_u64 v[238:239], v[236:237], 0, v[240:241]
	global_store_dwordx2 v[238:239], v[234:235], off
	v_cndmask_b32_e64 v24, v24, v26, s[6:7]
	v_xor_b32_e32 v26, 32, v185
	v_cmp_lt_i32_e32 vcc, v26, v68
	v_cndmask_b32_e64 v25, v25, v27, s[6:7]
	s_lshr_b32 s36, s33, 3
	v_cndmask_b32_e32 v26, v185, v26, vcc
	v_lshlrev_b32_e32 v26, 2, v26
	ds_bpermute_b32 v37, v26, v24
	ds_bpermute_b32 v36, v26, v25
	v_lshl_add_u64 v[24:25], v[32:33], 1, v[156:157]
	v_lshl_add_u64 v[24:25], v[24:25], 0, s[36:37]
	s_waitcnt lgkmcnt(0)
	v_and_or_b32 v232, v37, s62, v67
	v_or_b32_sdwa v233, v37, v64 dst_sel:DWORD dst_unused:UNUSED_PAD src0_sel:WORD_1 src1_sel:DWORD
	v_and_or_b32 v234, v36, s62, v65
	v_or_b32_sdwa v235, v36, v66 dst_sel:DWORD dst_unused:UNUSED_PAD src0_sel:WORD_1 src1_sel:DWORD
	v_lshl_or_b32 v236, v37, 16, v60
	v_and_or_b32 v237, v37, s63, v61
	v_lshl_or_b32 v238, v36, 16, v62
	v_and_or_b32 v239, v36, s63, v63
	v_mov_b32_e32 v240, 0x1000
	v_mov_b32_e32 v241, 0
	v_cndmask_b32_e64 v232, v236, v232, s[8:9]
	v_cndmask_b32_e64 v233, v237, v233, s[8:9]
	v_cndmask_b32_e64 v234, v238, v234, s[8:9]
	v_cndmask_b32_e64 v235, v239, v235, s[8:9]
	v_cndmask_b32_e64 v240, 0, v240, s[8:9]
	v_lshl_add_u64 v[24:25], v[24:25], 0, v[240:241]
	global_store_dword v[24:25], v232, off
	global_store_dword v[24:25], v233, off offset:1024
	global_store_dword v[24:25], v234, off offset:2048
	global_store_dword v[24:25], v235, off offset:3072
.LBB0_348:
	v_pk_mul_f32 v[22:23], v[22:23], v[46:47]
	v_pk_mul_f32 v[20:21], v[20:21], v[44:45]
	v_pk_mul_f32 v[24:25], v[18:19], v[42:43]
	v_pk_mul_f32 v[18:19], v[16:17], v[40:41]
	v_cvt_pk_bf16_f32 v16, v20, v21
	v_cvt_pk_bf16_f32 v17, v22, v23
	v_cvt_pk_bf16_f32 v18, v18, v19
	v_cvt_pk_bf16_f32 v19, v24, v25
	s_and_b64 vcc, exec, s[12:13]
	global_store_dwordx4 v[34:35], v[16:19], off offset:256
	s_cbranch_vccnz .LBB0_358
	v_and_b32_e32 v26, 64, v185
	v_xor_b32_e32 v22, 16, v185
	v_add_u32_e32 v56, 64, v26
	v_and_b32_e32 v30, 0xffff, v16
	s_waitcnt lgkmcnt(1)
	v_lshlrev_b32_e32 v39, 16, v18
	v_lshrrev_b32_e32 v31, 16, v16
	s_waitcnt lgkmcnt(0)
	v_and_b32_e32 v36, 0xffff0000, v18
	v_and_b32_e32 v34, 0xffff, v17
	v_lshlrev_b32_e32 v37, 16, v19
	v_lshrrev_b32_e32 v35, 16, v17
	v_and_b32_e32 v38, 0xffff0000, v19
	v_cmp_lt_i32_e32 vcc, v22, v56
	v_or_b32_e32 v24, v39, v30
	v_or_b32_e32 v58, v36, v31
	v_or_b32_e32 v23, v37, v34
	v_or_b32_e32 v21, v38, v35
	v_cndmask_b32_e32 v22, v185, v22, vcc
	v_cndmask_b32_e64 v20, v24, v23, s[2:3]
	v_cndmask_b32_e64 v25, v58, v21, s[2:3]
	v_lshlrev_b32_e32 v26, 2, v22
	ds_bpermute_b32 v22, v26, v20
	ds_bpermute_b32 v57, v26, v25
	s_or_b32 s34, s33, 0x80
	s_lshr_b32 s36, s34, 1
	v_lshl_add_u64 v[26:27], v[28:29], 0, s[36:37]
	v_lshl_add_u64 v[26:27], v[26:27], 0, v[152:153]
	s_waitcnt lgkmcnt(0)
	v_cndmask_b32_e64 v232, v24, v22, s[4:5]
	v_cndmask_b32_e64 v233, v22, v23, s[4:5]
	v_cndmask_b32_e64 v234, v58, v57, s[4:5]
	v_cndmask_b32_e64 v235, v57, v21, s[4:5]
	v_mov_b32_e32 v240, 0x2000
	v_mov_b32_e32 v241, 0
	v_cndmask_b32_e64 v240, 0, v240, s[4:5]
	v_lshl_add_u64 v[236:237], v[26:27], 0, v[240:241]
	global_store_dwordx2 v[236:237], v[232:233], off
	v_mov_b32_e32 v240, 0x1000
	v_lshl_add_u64 v[238:239], v[236:237], 0, v[240:241]
	global_store_dwordx2 v[238:239], v[234:235], off
	v_cndmask_b32_e64 v16, v16, v18, s[6:7]
	v_xor_b32_e32 v18, 32, v185
	v_cmp_lt_i32_e32 vcc, v18, v56
	v_cndmask_b32_e64 v17, v17, v19, s[6:7]
	s_lshr_b32 s36, s34, 3
	v_cndmask_b32_e32 v18, v185, v18, vcc
	v_lshlrev_b32_e32 v18, 2, v18
	ds_bpermute_b32 v23, v18, v16
	ds_bpermute_b32 v22, v18, v17
	v_lshl_add_u64 v[16:17], v[32:33], 1, v[156:157]
	v_lshl_add_u64 v[16:17], v[16:17], 0, s[36:37]
	s_waitcnt lgkmcnt(0)
	v_and_or_b32 v232, v23, s62, v39
	v_or_b32_sdwa v233, v23, v36 dst_sel:DWORD dst_unused:UNUSED_PAD src0_sel:WORD_1 src1_sel:DWORD
	v_and_or_b32 v234, v22, s62, v37
	v_or_b32_sdwa v235, v22, v38 dst_sel:DWORD dst_unused:UNUSED_PAD src0_sel:WORD_1 src1_sel:DWORD
	v_lshl_or_b32 v236, v23, 16, v30
	v_and_or_b32 v237, v23, s63, v31
	v_lshl_or_b32 v238, v22, 16, v34
	v_and_or_b32 v239, v22, s63, v35
	v_mov_b32_e32 v240, 0x1000
	v_mov_b32_e32 v241, 0
	v_cndmask_b32_e64 v232, v236, v232, s[8:9]
	v_cndmask_b32_e64 v233, v237, v233, s[8:9]
	v_cndmask_b32_e64 v234, v238, v234, s[8:9]
	v_cndmask_b32_e64 v235, v239, v235, s[8:9]
	v_cndmask_b32_e64 v240, 0, v240, s[8:9]
	v_lshl_add_u64 v[16:17], v[16:17], 0, v[240:241]
	global_store_dword v[16:17], v232, off
	global_store_dword v[16:17], v233, off offset:1024
	global_store_dword v[16:17], v234, off offset:2048
	global_store_dword v[16:17], v235, off offset:3072
.LBB0_358:
	s_nop 0
	v_add_u32_e32 v18, 0xb0, v186
	v_mov_b64_e32 v[16:17], s[28:29]
	v_mad_i64_i32 v[16:17], s[76:77], v18, s61, v[16:17]
	v_lshl_add_u64 v[18:19], v[168:169], 1, v[16:17]
	v_add_u32_e32 v20, 0xfffffeb0, v186
	v_mov_b64_e32 v[16:17], s[74:75]
	v_mad_i64_i32 v[16:17], s[74:75], v20, s54, v[16:17]
	v_pk_mul_f32 v[14:15], v[14:15], v[54:55]
	v_pk_mul_f32 v[12:13], v[12:13], v[52:53]
	v_pk_mul_f32 v[20:21], v[10:11], v[50:51]
	v_pk_mul_f32 v[10:11], v[8:9], v[48:49]
	v_cvt_pk_bf16_f32 v8, v12, v13
	v_cvt_pk_bf16_f32 v9, v14, v15
	v_cvt_pk_bf16_f32 v10, v10, v11
	v_cvt_pk_bf16_f32 v11, v20, v21
	s_and_b64 vcc, exec, s[12:13]
	v_lshl_add_u64 v[12:13], v[16:17], 1, s[20:21]
	global_store_dwordx4 v[18:19], v[8:11], off
	s_cbranch_vccnz .LBB0_368
	v_and_b32_e32 v24, 64, v185
	v_xor_b32_e32 v20, 16, v185
	s_waitcnt lgkmcnt(0)
	v_add_u32_e32 v36, 64, v24
	v_and_b32_e32 v28, 0xffff, v8
	v_lshlrev_b32_e32 v35, 16, v10
	v_lshrrev_b32_e32 v29, 16, v8
	v_and_b32_e32 v32, 0xffff0000, v10
	v_and_b32_e32 v30, 0xffff, v9
	v_lshlrev_b32_e32 v33, 16, v11
	v_lshrrev_b32_e32 v31, 16, v9
	v_and_b32_e32 v34, 0xffff0000, v11
	v_cmp_lt_i32_e32 vcc, v20, v36
	v_or_b32_e32 v22, v35, v28
	v_or_b32_e32 v37, v32, v29
	v_or_b32_e32 v21, v33, v30
	v_or_b32_e32 v15, v34, v31
	v_cndmask_b32_e32 v20, v185, v20, vcc
	v_cndmask_b32_e64 v14, v22, v21, s[2:3]
	v_cndmask_b32_e64 v23, v37, v15, s[2:3]
	v_lshlrev_b32_e32 v24, 2, v20
	ds_bpermute_b32 v20, v24, v14
	ds_bpermute_b32 v38, v24, v23
	s_lshr_b32 s36, s33, 1
	v_lshl_add_u64 v[24:25], v[12:13], 0, s[36:37]
	v_lshl_add_u64 v[24:25], v[24:25], 0, v[152:153]
	s_waitcnt lgkmcnt(0)
	v_cndmask_b32_e64 v232, v22, v20, s[4:5]
	v_cndmask_b32_e64 v233, v20, v21, s[4:5]
	v_cndmask_b32_e64 v234, v37, v38, s[4:5]
	v_cndmask_b32_e64 v235, v38, v15, s[4:5]
	v_mov_b32_e32 v240, 0x2000
	v_mov_b32_e32 v241, 0
	v_cndmask_b32_e64 v240, 0, v240, s[4:5]
	v_lshl_add_u64 v[236:237], v[24:25], 0, v[240:241]
	global_store_dwordx2 v[236:237], v[232:233], off
	v_mov_b32_e32 v240, 0x1000
	v_lshl_add_u64 v[238:239], v[236:237], 0, v[240:241]
	global_store_dwordx2 v[238:239], v[234:235], off
	v_cndmask_b32_e64 v8, v8, v10, s[6:7]
	v_xor_b32_e32 v10, 32, v185
	v_cmp_lt_i32_e32 vcc, v10, v36
	v_cndmask_b32_e64 v9, v9, v11, s[6:7]
	s_lshr_b32 s36, s33, 3
	v_cndmask_b32_e32 v10, v185, v10, vcc
	v_lshlrev_b32_e32 v10, 2, v10
	ds_bpermute_b32 v21, v10, v8
	ds_bpermute_b32 v20, v10, v9
	v_lshl_add_u64 v[8:9], v[16:17], 1, v[156:157]
	v_lshl_add_u64 v[8:9], v[8:9], 0, s[36:37]
	s_waitcnt lgkmcnt(0)
	v_and_or_b32 v232, v21, s62, v35
	v_or_b32_sdwa v233, v21, v32 dst_sel:DWORD dst_unused:UNUSED_PAD src0_sel:WORD_1 src1_sel:DWORD
	v_and_or_b32 v234, v20, s62, v33
	v_or_b32_sdwa v235, v20, v34 dst_sel:DWORD dst_unused:UNUSED_PAD src0_sel:WORD_1 src1_sel:DWORD
	v_lshl_or_b32 v236, v21, 16, v28
	v_and_or_b32 v237, v21, s63, v29
	v_lshl_or_b32 v238, v20, 16, v30
	v_and_or_b32 v239, v20, s63, v31
	v_mov_b32_e32 v240, 0x1000
	v_mov_b32_e32 v241, 0
	v_cndmask_b32_e64 v232, v236, v232, s[8:9]
	v_cndmask_b32_e64 v233, v237, v233, s[8:9]
	v_cndmask_b32_e64 v234, v238, v234, s[8:9]
	v_cndmask_b32_e64 v235, v239, v235, s[8:9]
	v_cndmask_b32_e64 v240, 0, v240, s[8:9]
	v_lshl_add_u64 v[8:9], v[8:9], 0, v[240:241]
	global_store_dword v[8:9], v232, off
	global_store_dword v[8:9], v233, off offset:1024
	global_store_dword v[8:9], v234, off offset:2048
	global_store_dword v[8:9], v235, off offset:3072
.LBB0_368:
	v_pk_mul_f32 v[6:7], v[6:7], v[46:47]
	v_pk_mul_f32 v[4:5], v[4:5], v[44:45]
	v_pk_mul_f32 v[8:9], v[2:3], v[42:43]
	v_pk_mul_f32 v[2:3], v[0:1], v[40:41]
	v_cvt_pk_bf16_f32 v0, v4, v5
	v_cvt_pk_bf16_f32 v1, v6, v7
	v_cvt_pk_bf16_f32 v2, v2, v3
	v_cvt_pk_bf16_f32 v3, v8, v9
	s_and_b64 vcc, exec, s[12:13]
	global_store_dwordx4 v[18:19], v[0:3], off offset:256
	s_cbranch_vccnz .LBB0_378
	v_and_b32_e32 v10, 64, v185
	v_xor_b32_e32 v6, 16, v185
	v_add_u32_e32 v24, 64, v10
	v_and_b32_e32 v14, 0xffff, v0
	s_waitcnt lgkmcnt(1)
	v_lshlrev_b32_e32 v23, 16, v2
	v_lshrrev_b32_e32 v15, 16, v0
	s_waitcnt lgkmcnt(0)
	v_and_b32_e32 v20, 0xffff0000, v2
	v_and_b32_e32 v18, 0xffff, v1
	v_lshlrev_b32_e32 v21, 16, v3
	v_lshrrev_b32_e32 v19, 16, v1
	v_and_b32_e32 v22, 0xffff0000, v3
	v_cmp_lt_i32_e32 vcc, v6, v24
	v_or_b32_e32 v8, v23, v14
	v_or_b32_e32 v25, v20, v15
	v_or_b32_e32 v7, v21, v18
	v_or_b32_e32 v5, v22, v19
	v_cndmask_b32_e32 v6, v185, v6, vcc
	v_cndmask_b32_e64 v4, v8, v7, s[2:3]
	v_cndmask_b32_e64 v9, v25, v5, s[2:3]
	v_lshlrev_b32_e32 v10, 2, v6
	ds_bpermute_b32 v6, v10, v4
	ds_bpermute_b32 v26, v10, v9
	s_bitset1_b32 s33, 7
	s_lshr_b32 s36, s33, 1
	v_lshl_add_u64 v[10:11], v[12:13], 0, s[36:37]
	v_lshl_add_u64 v[10:11], v[10:11], 0, v[152:153]
	s_waitcnt lgkmcnt(0)
	v_cndmask_b32_e64 v232, v8, v6, s[4:5]
	v_cndmask_b32_e64 v233, v6, v7, s[4:5]
	v_cndmask_b32_e64 v234, v25, v26, s[4:5]
	v_cndmask_b32_e64 v235, v26, v5, s[4:5]
	v_mov_b32_e32 v240, 0x2000
	v_mov_b32_e32 v241, 0
	v_cndmask_b32_e64 v240, 0, v240, s[4:5]
	v_lshl_add_u64 v[236:237], v[10:11], 0, v[240:241]
	global_store_dwordx2 v[236:237], v[232:233], off
	v_mov_b32_e32 v240, 0x1000
	v_lshl_add_u64 v[238:239], v[236:237], 0, v[240:241]
	global_store_dwordx2 v[238:239], v[234:235], off
	v_cndmask_b32_e64 v0, v0, v2, s[6:7]
	v_xor_b32_e32 v2, 32, v185
	v_cmp_lt_i32_e32 vcc, v2, v24
	v_cndmask_b32_e64 v1, v1, v3, s[6:7]
	s_lshr_b32 s36, s33, 3
	v_cndmask_b32_e32 v2, v185, v2, vcc
	v_lshlrev_b32_e32 v2, 2, v2
	ds_bpermute_b32 v7, v2, v0
	ds_bpermute_b32 v6, v2, v1
	v_lshl_add_u64 v[0:1], v[16:17], 1, v[156:157]
	v_lshl_add_u64 v[0:1], v[0:1], 0, s[36:37]
	s_waitcnt lgkmcnt(0)
	v_and_or_b32 v232, v7, s62, v23
	v_or_b32_sdwa v233, v7, v20 dst_sel:DWORD dst_unused:UNUSED_PAD src0_sel:WORD_1 src1_sel:DWORD
	v_and_or_b32 v234, v6, s62, v21
	v_or_b32_sdwa v235, v6, v22 dst_sel:DWORD dst_unused:UNUSED_PAD src0_sel:WORD_1 src1_sel:DWORD
	v_lshl_or_b32 v236, v7, 16, v14
	v_and_or_b32 v237, v7, s63, v15
	v_lshl_or_b32 v238, v6, 16, v18
	v_and_or_b32 v239, v6, s63, v19
	v_mov_b32_e32 v240, 0x1000
	v_mov_b32_e32 v241, 0
	v_cndmask_b32_e64 v232, v236, v232, s[8:9]
	v_cndmask_b32_e64 v233, v237, v233, s[8:9]
	v_cndmask_b32_e64 v234, v238, v234, s[8:9]
	v_cndmask_b32_e64 v235, v239, v235, s[8:9]
	v_cndmask_b32_e64 v240, 0, v240, s[8:9]
	v_lshl_add_u64 v[0:1], v[0:1], 0, v[240:241]
	global_store_dword v[0:1], v232, off
	global_store_dword v[0:1], v233, off offset:1024
	global_store_dword v[0:1], v234, off offset:2048
	global_store_dword v[0:1], v235, off offset:3072
